# grid barrier: follower workgroups issue the agent acquire (L1 invalidate) before polling instead of after
# speedup vs baseline: 1.0218x; 1.0094x over previous
; __device__ __forceinline__ unsigned xb_ld(unsigned* p)              { return __hip_atomic_load(p, __ATOMIC_RELAXED, __HIP_MEMORY_SCOPE_AGENT); }
; __device__ __forceinline__ unsigned xb_add(unsigned* p, unsigned v) { return __hip_atomic_fetch_add(p, v, __ATOMIC_RELAXED, __HIP_MEMORY_SCOPE_AGENT); }
; #define XB_SPIN(cond, bar) do { unsigned _sp = 0; while (cond) { __builtin_amdgcn_s_sleep(1); \
;     if ((++_sp & 255u) == 0u) { if (xb_ld(&(bar)[XB_TMO])) break; if (_sp > XB_SPIN_CAP) { atomicAdd(&(bar)[XB_TMO], 1u); break; } } } } while (0)
; __device__ __forceinline__ void xcd_barrier(const XcdBarrier& b) {
;     ...
;         unsigned nloc = b.st[0], nx = b.st[1];
;         if (nloc == 0u) { xcd_barrier_complete(bar, b.x, nloc, nx); b.st[0] = nloc; b.st[1] = nx; }
;         const unsigned old = xb_add(&bar[XB_XSUB(b.x)], 1u);
;         const unsigned gen = old / nloc;
;         if (old + 1u == (gen + 1u) * nloc) {
;             __builtin_amdgcn_fence(__ATOMIC_RELEASE, "agent");
;             asm volatile("s_waitcnt vmcnt(0)" ::: "memory");
;             const unsigned og = xb_add(&bar[XB_TOP], 1u);
;             const unsigned tg = og / nx;
;             if (og + 1u == (tg + 1u) * nx) xb_add(&bar[XB_TOPGEN], 1u);
;             else XB_SPIN(xb_ld(&bar[XB_TOPGEN]) == tg, bar);
;             __builtin_amdgcn_fence(__ATOMIC_ACQUIRE, "agent");
;             xb_add(&bar[XB_XGEN(b.x)], 1u);
;             asm volatile("s_waitcnt vmcnt(0)" ::: "memory");
;         } else {
;             XB_SPIN(xb_ld(&bar[XB_XGEN(b.x)]) == gen, bar);
;             __builtin_amdgcn_fence(__ATOMIC_ACQUIRE, "agent");
.LBB0_97:
	s_or_b64 exec, exec, s[10:11]
	v_cvt_f32_u32_e32 v5, v3
	s_waitcnt vmcnt(0)
	v_readfirstlane_b32 s0, v4
	v_sub_u32_e32 v4, 0, v3
	v_rcp_iflag_f32_e32 v5, v5
	v_add_u32_e32 v6, s0, v2
	v_mul_f32_e32 v5, 0x4f7ffffe, v5
	v_cvt_u32_f32_e32 v5, v5
	v_mul_lo_u32 v2, v4, v5
	v_mul_hi_u32 v2, v5, v2
	v_add_u32_e32 v2, v5, v2
	v_mul_hi_u32 v2, v6, v2
	v_mul_lo_u32 v4, v2, v3
	v_sub_u32_e32 v4, v6, v4
	v_add_u32_e32 v5, 1, v2
	v_cmp_ge_u32_e32 vcc, v4, v3
	s_nop 1
	v_cndmask_b32_e32 v2, v2, v5, vcc
	v_sub_u32_e32 v5, v4, v3
	v_cndmask_b32_e32 v4, v4, v5, vcc
	v_add_u32_e32 v5, 1, v2
	v_cmp_ge_u32_e32 vcc, v4, v3
	v_add_u32_e32 v4, 1, v6
	s_nop 0
	v_cndmask_b32_e32 v2, v2, v5, vcc
	v_mul_lo_u32 v5, v3, v2
	v_add_u32_e32 v3, v5, v3
	v_cmp_ne_u32_e32 vcc, v4, v3
	s_and_saveexec_b64 s[0:1], vcc
	s_xor_b64 s[8:9], exec, s[0:1]
	s_cbranch_execz .LBB0_111
	s_waitcnt lgkmcnt(0)
	buffer_inv sc1
	v_mov_b32_e32 v1, 0x2000
	global_load_dword v1, v1, s[6:7] offset:1024 sc1
	s_add_u32 s12, s6, 0x2400
	s_addc_u32 s13, s7, 0
	s_waitcnt vmcnt(0)
	v_cmp_eq_u32_e32 vcc, v1, v2
	s_and_saveexec_b64 s[10:11], vcc
	s_cbranch_execz .LBB0_110
	s_mov_b32 s0, 1
	s_mov_b64 s[14:15], 0
	v_mov_b32_e32 v1, 0
	s_branch .LBB0_101

; __device__ __forceinline__ unsigned xb_ld(unsigned* p)              { return __hip_atomic_load(p, __ATOMIC_RELAXED, __HIP_MEMORY_SCOPE_AGENT); }
; #define XB_SPIN(cond, bar) do { unsigned _sp = 0; while (cond) { __builtin_amdgcn_s_sleep(1); \
;     if ((++_sp & 255u) == 0u) { if (xb_ld(&(bar)[XB_TMO])) break; if (_sp > XB_SPIN_CAP) { atomicAdd(&(bar)[XB_TMO], 1u); break; } } } } while (0)
; __device__ __forceinline__ void xcd_barrier(const XcdBarrier& b) {
;     ...
;         } else {
;             XB_SPIN(xb_ld(&bar[XB_XGEN(b.x)]) == gen, bar);
;             __builtin_amdgcn_fence(__ATOMIC_ACQUIRE, "agent");
;             asm volatile("s_waitcnt vmcnt(0)" ::: "memory");
.LBB0_110:
	s_or_b64 exec, exec, s[10:11]
	s_waitcnt vmcnt(0)
	s_waitcnt vmcnt(0)

; __device__ __forceinline__ unsigned xb_ld(unsigned* p)              { return __hip_atomic_load(p, __ATOMIC_RELAXED, __HIP_MEMORY_SCOPE_AGENT); }
; __device__ __forceinline__ unsigned xb_add(unsigned* p, unsigned v) { return __hip_atomic_fetch_add(p, v, __ATOMIC_RELAXED, __HIP_MEMORY_SCOPE_AGENT); }
; #define XB_SPIN(cond, bar) do { unsigned _sp = 0; while (cond) { __builtin_amdgcn_s_sleep(1); \
;     if ((++_sp & 255u) == 0u) { if (xb_ld(&(bar)[XB_TMO])) break; if (_sp > XB_SPIN_CAP) { atomicAdd(&(bar)[XB_TMO], 1u); break; } } } } while (0)
; __device__ __forceinline__ void xcd_barrier(const XcdBarrier& b) {
;     ...
;         unsigned nloc = b.st[0], nx = b.st[1];
;         if (nloc == 0u) { xcd_barrier_complete(bar, b.x, nloc, nx); b.st[0] = nloc; b.st[1] = nx; }
;         const unsigned old = xb_add(&bar[XB_XSUB(b.x)], 1u);
;         const unsigned gen = old / nloc;
;         if (old + 1u == (gen + 1u) * nloc) {
;             __builtin_amdgcn_fence(__ATOMIC_RELEASE, "agent");
;             asm volatile("s_waitcnt vmcnt(0)" ::: "memory");
;             const unsigned og = xb_add(&bar[XB_TOP], 1u);
;             const unsigned tg = og / nx;
;             if (og + 1u == (tg + 1u) * nx) xb_add(&bar[XB_TOPGEN], 1u);
;             else XB_SPIN(xb_ld(&bar[XB_TOPGEN]) == tg, bar);
;             __builtin_amdgcn_fence(__ATOMIC_ACQUIRE, "agent");
;             xb_add(&bar[XB_XGEN(b.x)], 1u);
;             asm volatile("s_waitcnt vmcnt(0)" ::: "memory");
;         } else {
;             XB_SPIN(xb_ld(&bar[XB_XGEN(b.x)]) == gen, bar);
;             __builtin_amdgcn_fence(__ATOMIC_ACQUIRE, "agent");
.LBB0_1016:
	s_or_b64 exec, exec, s[8:9]
	v_cvt_f32_u32_e32 v5, v3
	s_waitcnt vmcnt(0)
	v_readfirstlane_b32 s0, v4
	v_sub_u32_e32 v4, 0, v3
	v_rcp_iflag_f32_e32 v5, v5
	v_add_u32_e32 v6, s0, v2
	v_mul_f32_e32 v5, 0x4f7ffffe, v5
	v_cvt_u32_f32_e32 v5, v5
	v_mul_lo_u32 v2, v4, v5
	v_mul_hi_u32 v2, v5, v2
	v_add_u32_e32 v2, v5, v2
	v_mul_hi_u32 v2, v6, v2
	v_mul_lo_u32 v4, v2, v3
	v_sub_u32_e32 v4, v6, v4
	v_add_u32_e32 v5, 1, v2
	v_cmp_ge_u32_e32 vcc, v4, v3
	s_nop 1
	v_cndmask_b32_e32 v2, v2, v5, vcc
	v_sub_u32_e32 v5, v4, v3
	v_cndmask_b32_e32 v4, v4, v5, vcc
	v_add_u32_e32 v5, 1, v2
	v_cmp_ge_u32_e32 vcc, v4, v3
	v_add_u32_e32 v4, 1, v6
	s_nop 0
	v_cndmask_b32_e32 v2, v2, v5, vcc
	v_mul_lo_u32 v5, v3, v2
	v_add_u32_e32 v3, v5, v3
	v_cmp_ne_u32_e32 vcc, v4, v3
	s_and_saveexec_b64 s[0:1], vcc
	s_xor_b64 s[6:7], exec, s[0:1]
	s_cbranch_execz .LBB0_1030
	s_waitcnt lgkmcnt(0)
	buffer_inv sc1
	v_mov_b32_e32 v1, 0x2000
	global_load_dword v1, v1, s[4:5] offset:1024 sc1
	s_add_u32 s10, s4, 0x2400
	s_addc_u32 s11, s5, 0
	s_waitcnt vmcnt(0)
	v_cmp_eq_u32_e32 vcc, v1, v2
	s_and_saveexec_b64 s[8:9], vcc
	s_cbranch_execz .LBB0_1029
	s_mov_b32 s0, 1
	s_mov_b64 s[12:13], 0
	v_mov_b32_e32 v1, 0
	s_branch .LBB0_1020

; __device__ __forceinline__ unsigned xb_ld(unsigned* p)              { return __hip_atomic_load(p, __ATOMIC_RELAXED, __HIP_MEMORY_SCOPE_AGENT); }
; #define XB_SPIN(cond, bar) do { unsigned _sp = 0; while (cond) { __builtin_amdgcn_s_sleep(1); \
;     if ((++_sp & 255u) == 0u) { if (xb_ld(&(bar)[XB_TMO])) break; if (_sp > XB_SPIN_CAP) { atomicAdd(&(bar)[XB_TMO], 1u); break; } } } } while (0)
; __device__ __forceinline__ void xcd_barrier(const XcdBarrier& b) {
;     ...
;         } else {
;             XB_SPIN(xb_ld(&bar[XB_XGEN(b.x)]) == gen, bar);
;             __builtin_amdgcn_fence(__ATOMIC_ACQUIRE, "agent");
;             asm volatile("s_waitcnt vmcnt(0)" ::: "memory");
.LBB0_1029:
	s_or_b64 exec, exec, s[8:9]
	s_waitcnt vmcnt(0)
	s_waitcnt vmcnt(0)
